# code placement: the four GEMM K-loop heads aligned to 64 bytes (s_nop padding)
# speedup vs baseline: 1.0004x; 1.0004x over previous
.LBB0_125:
	s_and_b64 s[36:37], s[28:29], exec
	s_cselect_b32 s5, s25, s31
	s_cselect_b32 s38, s24, s30
	s_cselect_b32 s39, s27, s35
	s_cselect_b32 s44, s26, s34
	s_add_u32 s30, s30, 0x40080
	s_addc_u32 s31, s31, 0
	s_add_u32 s45, s34, 0x100
	v_mov_b32_e32 v2, 0
	s_addc_u32 s71, s35, 0
	s_mov_b32 s72, -2
	v_mov_b32_e32 v3, v2
	v_mov_b32_e32 v4, v2
	v_mov_b32_e32 v5, v2
	v_mov_b32_e32 v6, v2
	v_mov_b32_e32 v7, v2
	v_mov_b32_e32 v8, v2
	v_mov_b32_e32 v9, v2
	v_mov_b32_e32 v18, v2
	v_mov_b32_e32 v19, v2
	v_mov_b32_e32 v20, v2
	v_mov_b32_e32 v21, v2
	v_mov_b32_e32 v22, v2
	v_mov_b32_e32 v23, v2
	v_mov_b32_e32 v24, v2
	v_mov_b32_e32 v25, v2
	v_mov_b32_e32 v34, v2
	v_mov_b32_e32 v35, v2
	v_mov_b32_e32 v36, v2
	v_mov_b32_e32 v37, v2
	v_mov_b32_e32 v38, v2
	v_mov_b32_e32 v39, v2
	v_mov_b32_e32 v40, v2
	v_mov_b32_e32 v41, v2
	v_mov_b32_e32 v50, v2
	v_mov_b32_e32 v51, v2
	v_mov_b32_e32 v52, v2
	v_mov_b32_e32 v53, v2
	v_mov_b32_e32 v54, v2
	v_mov_b32_e32 v55, v2
	v_mov_b32_e32 v56, v2
	v_mov_b32_e32 v57, v2
	v_mov_b32_e32 v10, v2
	v_mov_b32_e32 v11, v2
	v_mov_b32_e32 v12, v2
	v_mov_b32_e32 v13, v2
	v_mov_b32_e32 v14, v2
	v_mov_b32_e32 v15, v2
	v_mov_b32_e32 v16, v2
	v_mov_b32_e32 v17, v2
	v_mov_b32_e32 v26, v2
	v_mov_b32_e32 v27, v2
	v_mov_b32_e32 v28, v2
	v_mov_b32_e32 v29, v2
	v_mov_b32_e32 v30, v2
	v_mov_b32_e32 v31, v2
	v_mov_b32_e32 v32, v2
	v_mov_b32_e32 v33, v2
	v_mov_b32_e32 v42, v2
	v_mov_b32_e32 v43, v2
	v_mov_b32_e32 v44, v2
	v_mov_b32_e32 v45, v2
	v_mov_b32_e32 v46, v2
	v_mov_b32_e32 v47, v2
	v_mov_b32_e32 v48, v2
	v_mov_b32_e32 v49, v2
	v_mov_b32_e32 v58, v2
	v_mov_b32_e32 v59, v2
	v_mov_b32_e32 v60, v2
	v_mov_b32_e32 v61, v2
	v_mov_b32_e32 v62, v2
	v_mov_b32_e32 v63, v2
	v_mov_b32_e32 v64, v2
	v_mov_b32_e32 v65, v2
	v_mov_b32_e32 v66, v2
	v_mov_b32_e32 v67, v2
	v_mov_b32_e32 v68, v2
	v_mov_b32_e32 v69, v2
	v_mov_b32_e32 v70, v2
	v_mov_b32_e32 v71, v2
	v_mov_b32_e32 v72, v2
	v_mov_b32_e32 v73, v2
	v_mov_b32_e32 v82, v2
	v_mov_b32_e32 v83, v2
	v_mov_b32_e32 v84, v2
	v_mov_b32_e32 v85, v2
	v_mov_b32_e32 v86, v2
	v_mov_b32_e32 v87, v2
	v_mov_b32_e32 v88, v2
	v_mov_b32_e32 v89, v2
	v_mov_b32_e32 v98, v2
	v_mov_b32_e32 v99, v2
	v_mov_b32_e32 v100, v2
	v_mov_b32_e32 v101, v2
	v_mov_b32_e32 v102, v2
	v_mov_b32_e32 v103, v2
	v_mov_b32_e32 v104, v2
	v_mov_b32_e32 v105, v2
	v_mov_b32_e32 v114, v2
	v_mov_b32_e32 v115, v2
	v_mov_b32_e32 v116, v2
	v_mov_b32_e32 v117, v2
	v_mov_b32_e32 v118, v2
	v_mov_b32_e32 v119, v2
	v_mov_b32_e32 v120, v2
	v_mov_b32_e32 v121, v2
	v_mov_b32_e32 v74, v2
	v_mov_b32_e32 v75, v2
	v_mov_b32_e32 v76, v2
	v_mov_b32_e32 v77, v2
	v_mov_b32_e32 v78, v2
	v_mov_b32_e32 v79, v2
	v_mov_b32_e32 v80, v2
	v_mov_b32_e32 v81, v2
	v_mov_b32_e32 v90, v2
	v_mov_b32_e32 v91, v2
	v_mov_b32_e32 v92, v2
	v_mov_b32_e32 v93, v2
	v_mov_b32_e32 v94, v2
	v_mov_b32_e32 v95, v2
	v_mov_b32_e32 v96, v2
	v_mov_b32_e32 v97, v2
	v_mov_b32_e32 v106, v2
	v_mov_b32_e32 v107, v2
	v_mov_b32_e32 v108, v2
	v_mov_b32_e32 v109, v2
	v_mov_b32_e32 v110, v2
	v_mov_b32_e32 v111, v2
	v_mov_b32_e32 v112, v2
	v_mov_b32_e32 v113, v2
	v_mov_b32_e32 v122, v2
	v_mov_b32_e32 v123, v2
	v_mov_b32_e32 v124, v2
	v_mov_b32_e32 v125, v2
	v_mov_b32_e32 v126, v2
	v_mov_b32_e32 v127, v2
	v_mov_b32_e32 v128, v2
	v_mov_b32_e32 v129, v2
	.p2alignl 6, 3212836864

.LBB0_760:
	s_add_u32 s21, s26, 0x100
	s_addc_u32 s66, s27, 0
	v_lshl_add_u64 v[146:147], s[16:17], 0, v[138:139]
	v_lshl_add_u64 v[148:149], s[16:17], 0, v[140:141]
	s_mov_b32 s67, -2
	s_mov_b64 s[26:27], 0
	.p2alignl 6, 3212836864

.LBB0_964:
	s_and_b64 s[12:13], s[38:39], exec
	s_cselect_b32 s50, s35, s15
	s_cselect_b32 s51, s34, s14
	s_cselect_b32 s54, s37, s41
	s_cselect_b32 s55, s36, s40
	s_cmp_eq_u32 s31, 0
	s_cselect_b64 vcc, -1, 0
	s_and_b64 s[12:13], vcc, exec
	s_cselect_b32 s56, 0, s19
	s_cselect_b32 s86, 0x40000, s18
	s_add_u32 s12, s14, 0x40080
	s_addc_u32 s13, s15, 0
	s_add_u32 s87, s40, 0x100
	v_mov_b32_e32 v0, 0
	v_cndmask_b32_e32 v128, v193, v192, vcc
	v_cndmask_b32_e32 v129, v191, v140, vcc
	s_addc_u32 s88, s41, 0
	s_mov_b32 s89, -2
	v_mov_b32_e32 v1, v0
	v_mov_b32_e32 v2, v0
	v_mov_b32_e32 v3, v0
	v_mov_b32_e32 v4, v0
	v_mov_b32_e32 v5, v0
	v_mov_b32_e32 v6, v0
	v_mov_b32_e32 v7, v0
	v_mov_b32_e32 v16, v0
	v_mov_b32_e32 v17, v0
	v_mov_b32_e32 v18, v0
	v_mov_b32_e32 v19, v0
	v_mov_b32_e32 v20, v0
	v_mov_b32_e32 v21, v0
	v_mov_b32_e32 v22, v0
	v_mov_b32_e32 v23, v0
	v_mov_b32_e32 v32, v0
	v_mov_b32_e32 v33, v0
	v_mov_b32_e32 v34, v0
	v_mov_b32_e32 v35, v0
	v_mov_b32_e32 v36, v0
	v_mov_b32_e32 v37, v0
	v_mov_b32_e32 v38, v0
	v_mov_b32_e32 v39, v0
	v_mov_b32_e32 v48, v0
	v_mov_b32_e32 v49, v0
	v_mov_b32_e32 v50, v0
	v_mov_b32_e32 v51, v0
	v_mov_b32_e32 v52, v0
	v_mov_b32_e32 v53, v0
	v_mov_b32_e32 v54, v0
	v_mov_b32_e32 v55, v0
	v_mov_b32_e32 v8, v0
	v_mov_b32_e32 v9, v0
	v_mov_b32_e32 v10, v0
	v_mov_b32_e32 v11, v0
	v_mov_b32_e32 v12, v0
	v_mov_b32_e32 v13, v0
	v_mov_b32_e32 v14, v0
	v_mov_b32_e32 v15, v0
	v_mov_b32_e32 v24, v0
	v_mov_b32_e32 v25, v0
	v_mov_b32_e32 v26, v0
	v_mov_b32_e32 v27, v0
	v_mov_b32_e32 v28, v0
	v_mov_b32_e32 v29, v0
	v_mov_b32_e32 v30, v0
	v_mov_b32_e32 v31, v0
	v_mov_b32_e32 v40, v0
	v_mov_b32_e32 v41, v0
	v_mov_b32_e32 v42, v0
	v_mov_b32_e32 v43, v0
	v_mov_b32_e32 v44, v0
	v_mov_b32_e32 v45, v0
	v_mov_b32_e32 v46, v0
	v_mov_b32_e32 v47, v0
	v_mov_b32_e32 v56, v0
	v_mov_b32_e32 v57, v0
	v_mov_b32_e32 v58, v0
	v_mov_b32_e32 v59, v0
	v_mov_b32_e32 v60, v0
	v_mov_b32_e32 v61, v0
	v_mov_b32_e32 v62, v0
	v_mov_b32_e32 v63, v0
	v_mov_b32_e32 v64, v0
	v_mov_b32_e32 v65, v0
	v_mov_b32_e32 v66, v0
	v_mov_b32_e32 v67, v0
	v_mov_b32_e32 v68, v0
	v_mov_b32_e32 v69, v0
	v_mov_b32_e32 v70, v0
	v_mov_b32_e32 v71, v0
	v_mov_b32_e32 v80, v0
	v_mov_b32_e32 v81, v0
	v_mov_b32_e32 v82, v0
	v_mov_b32_e32 v83, v0
	v_mov_b32_e32 v84, v0
	v_mov_b32_e32 v85, v0
	v_mov_b32_e32 v86, v0
	v_mov_b32_e32 v87, v0
	v_mov_b32_e32 v96, v0
	v_mov_b32_e32 v97, v0
	v_mov_b32_e32 v98, v0
	v_mov_b32_e32 v99, v0
	v_mov_b32_e32 v100, v0
	v_mov_b32_e32 v101, v0
	v_mov_b32_e32 v102, v0
	v_mov_b32_e32 v103, v0
	v_mov_b32_e32 v112, v0
	v_mov_b32_e32 v113, v0
	v_mov_b32_e32 v114, v0
	v_mov_b32_e32 v115, v0
	v_mov_b32_e32 v116, v0
	v_mov_b32_e32 v117, v0
	v_mov_b32_e32 v118, v0
	v_mov_b32_e32 v119, v0
	v_mov_b32_e32 v72, v0
	v_mov_b32_e32 v73, v0
	v_mov_b32_e32 v74, v0
	v_mov_b32_e32 v75, v0
	v_mov_b32_e32 v76, v0
	v_mov_b32_e32 v77, v0
	v_mov_b32_e32 v78, v0
	v_mov_b32_e32 v79, v0
	v_mov_b32_e32 v88, v0
	v_mov_b32_e32 v89, v0
	v_mov_b32_e32 v90, v0
	v_mov_b32_e32 v91, v0
	v_mov_b32_e32 v92, v0
	v_mov_b32_e32 v93, v0
	v_mov_b32_e32 v94, v0
	v_mov_b32_e32 v95, v0
	v_mov_b32_e32 v104, v0
	v_mov_b32_e32 v105, v0
	v_mov_b32_e32 v106, v0
	v_mov_b32_e32 v107, v0
	v_mov_b32_e32 v108, v0
	v_mov_b32_e32 v109, v0
	v_mov_b32_e32 v110, v0
	v_mov_b32_e32 v111, v0
	v_mov_b32_e32 v120, v0
	v_mov_b32_e32 v121, v0
	v_mov_b32_e32 v122, v0
	v_mov_b32_e32 v123, v0
	v_mov_b32_e32 v124, v0
	v_mov_b32_e32 v125, v0
	v_mov_b32_e32 v126, v0
	v_mov_b32_e32 v127, v0
	.p2alignl 6, 3212836864

.LBB0_1510:
	s_add_u32 s21, s26, 0x100
	s_addc_u32 s55, s27, 0
	v_lshl_add_u64 v[144:145], s[16:17], 0, v[136:137]
	v_lshl_add_u64 v[146:147], s[16:17], 0, v[138:139]
	s_mov_b32 s56, -2
	s_mov_b64 s[26:27], 0
	.p2alignl 6, 3212836864
